# A/B: one static s_setprio 1 for waves 4-7 (younger half) during each GEMM phase, reset at phase end; no per-segment flips
# baseline (speedup 1.0000x reference)
;     __host__ __device__ bool next(int i, Unit& u) const { if (!base.next(i >> 1, u)) return false; if (i & 1) { u.pm += 64; u.pn += 8; } return true; }
; #define PG8_STAGE(bufoff, gbase, voff) do { _Pragma("unroll") for (int _i = 0; _i < 2; ++_i) \
;         __builtin_amdgcn_global_load_lds((const unsigned*)((const char*)(gbase) + (voff)[_i]), (PG8_LAS unsigned*)(lds + (bufoff) + ldsw + _i * 8192), 16, 0, 0); } while (0)
; #define PG8_WAIT_V(n) asm volatile("s_waitcnt vmcnt(" #n ")" ::: "memory")
; #define PG8_BAR __builtin_amdgcn_s_barrier()
; template <class Epi, class Sched, bool ALIGN_EPI = false, bool SP2 = false>
; __device__ __forceinline__ void gemm_phase(PG8_LAS unsigned char* lds, const Gemm g, const Sched& S, const Epi& E) {
;     ...
;     const int aoff = lds_byte(wr * 64 + fr, fq * 8), boff = lds_byte(wc * 32 + fr, fq * 8);
;     ...
;     Unit cur, nxt; int ui = 0;
;     if (!S.next(0, cur)) return;
;     f32x4 acc[2][2][4][2];
; #pragma unroll
;     for (int a = 0; a < 2; ++a)
; #pragma unroll
;         for (int b = 0; b < 2; ++b)
; #pragma unroll
;             for (int m = 0; m < 4; ++m)
; #pragma unroll
;                 for (int n = 0; n < 2; ++n) acc[a][b][m][n] = (f32x4){0.f, 0.f, 0.f, 0.f};
;     bf16x8 At[4][2], B0[2][2], B1[2][2];
;     const char* cA = (const char*)g.A + (size_t)cur.pm * tstep; const char* cB = (const char*)g.Bt + (size_t)cur.pn * tstep;
;     S.a_ready(cur);
;     if constexpr (SP2) {
;         PG8_STAGE(PG8_SB(0, 0), cB, voffB); PG8_STAGE(PG8_SB(0, 1), cB + hstep, voffB); PG8_STAGE(PG8_SA(0, 0), cA, voffA); PG8_STAGE(PG8_SA(0, 1), cA + hstep, voffA);
;         if (wr == 1) PG8_BAR;
;         PG8_WAIT_V(2); PG8_BAR;
;         PG8_STAGE(PG8_SB(1, 0), cB + kstep, voffB); PG8_STAGE(PG8_SA(1, 0), cA + kstep, voffA); PG8_STAGE(PG8_SB(1, 1), cB + hstep + kstep, voffB);
;         PG8_WAIT_V(6); PG8_BAR;
.LBB0_19:
	v_lshrrev_b32_e32 v16, 1, v6
	v_and_b32_e32 v16, 24, v16
	v_and_b32_e32 v7, 15, v6
	v_lshlrev_b32_e32 v17, 1, v16
	v_lshlrev_b32_e32 v6, 2, v6
	s_sext_i32_i8 s82, s24
	v_lshl_or_b32 v138, s54, 6, v7
	v_lshl_or_b32 v7, v7, 6, v17
	s_lshl_b32 s24, s54, 13
	v_and_b32_e32 v6, 32, v6
	v_bitop3_b32 v17, v7, s24, v6 bitop3:0xde
	s_lshl_b32 s24, s43, 5
	s_and_b32 s63, s24, 0x60
	v_lshl_add_u64 v[8:9], s[4:5], 0, v[160:161]
	v_mov_b32_e32 v129, v161
	s_lshl_b32 s24, s63, 7
	v_lshl_add_u64 v[10:11], s[4:5], 0, v[128:129]
	v_mov_b32_e32 v133, v161
	v_bitop3_b32 v139, v7, s24, v6 bitop3:0xde
	s_add_i32 m0, s29, 0x18000
	v_lshl_add_u64 v[6:7], v[8:9], 0, s[30:31]
	v_lshl_add_u64 v[12:13], s[52:53], 0, v[132:133]
	v_mov_b32_e32 v131, v161
	s_waitcnt vmcnt(2)
	s_barrier
	global_load_lds_dwordx4 v[6:7], off
	v_lshl_add_u64 v[6:7], v[10:11], 0, s[30:31]
	s_add_i32 m0, s29, 0x1a000
	s_add_i32 s24, s29, 0x8000
	s_add_i32 s59, s29, 0xa000
	v_lshl_add_u64 v[14:15], s[52:53], 0, v[130:131]
	global_load_lds_dwordx4 v[6:7], off
	v_lshl_add_u64 v[6:7], v[12:13], 0, s[30:31]
	s_mov_b32 m0, s24
	s_add_u32 s54, s4, 0x80080
	global_load_lds_dwordx4 v[6:7], off
	v_lshl_add_u64 v[6:7], v[14:15], 0, s[30:31]
	s_mov_b32 m0, s59
	s_addc_u32 s55, s5, 0
	global_load_lds_dwordx4 v[6:7], off
	s_add_i32 m0, s29, 0x1c000
	v_lshl_add_u64 v[6:7], s[54:55], 0, v[160:161]
	global_load_lds_dwordx4 v[6:7], off
	v_lshl_add_u64 v[6:7], s[54:55], 0, v[128:129]
	s_add_i32 m0, s29, 0x1e000
	s_cmpk_lt_u32 s42, 0x100
	global_load_lds_dwordx4 v[6:7], off
	v_lshlrev_b32_e32 v6, 15, v4
	v_and_b32_e32 v6, 0xffff0000, v6
	v_lshl_add_u32 v3, v3, 12, v6
	v_and_b32_e32 v4, 1, v4
	v_lshl_or_b32 v3, v4, 6, v3
	v_lshl_add_u32 v134, v5, 1, v3
	v_lshlrev_b32_e32 v3, 15, v0
	v_and_b32_e32 v3, 0xffff0000, v3
	s_waitcnt vmcnt(6)
	v_lshl_add_u32 v1, v1, 12, v3
	v_and_b32_e32 v0, 1, v0
	v_lshl_or_b32 v0, v0, 6, v1
	s_cselect_b64 s[42:43], -1, 0
	v_or_b32_e32 v140, s63, v16
	v_mov_b32_e32 v135, v161
	v_lshl_add_u32 v136, v2, 1, v0
	v_mov_b32_e32 v137, v161
	v_readlane_b32 s98, v254, 19
	s_nop 3
	s_cmp_ge_u32 s98, 4
	s_cbranch_scc0 .Lyh_out
	s_setprio 1
.Lyh_out:
	s_mov_b32 s63, 0
	v_add_u32_e32 v141, 0, v17
	s_barrier
	s_branch .LBB0_22

;     __host__ __device__ bool next(int i, Unit& u) const { if (!base.next(i >> 1, u)) return false; if (i & 1) { u.pm += 64; u.pn += 8; } return true; }
; #define PG8_STAGE(bufoff, gbase, voff) do { _Pragma("unroll") for (int _i = 0; _i < 2; ++_i) \
;         __builtin_amdgcn_global_load_lds((const unsigned*)((const char*)(gbase) + (voff)[_i]), (PG8_LAS unsigned*)(lds + (bufoff) + ldsw + _i * 8192), 16, 0, 0); } while (0)
; #define PG8_WAIT_V(n) asm volatile("s_waitcnt vmcnt(" #n ")" ::: "memory")
; #define PG8_BAR __builtin_amdgcn_s_barrier()
; template <class Epi, class Sched, bool ALIGN_EPI = false, bool SP2 = false>
; __device__ __forceinline__ void gemm_phase(PG8_LAS unsigned char* lds, const Gemm g, const Sched& S, const Epi& E) {
;     ...
;     const int aoff = lds_byte(wr * 64 + fr, fq * 8), boff = lds_byte(wc * 32 + fr, fq * 8);
;     ...
;     Unit cur, nxt; int ui = 0;
;     if (!S.next(0, cur)) return;
;     f32x4 acc[2][2][4][2];
; #pragma unroll
;     for (int a = 0; a < 2; ++a)
; #pragma unroll
;         for (int b = 0; b < 2; ++b)
; #pragma unroll
;             for (int m = 0; m < 4; ++m)
; #pragma unroll
;                 for (int n = 0; n < 2; ++n) acc[a][b][m][n] = (f32x4){0.f, 0.f, 0.f, 0.f};
;     bf16x8 At[4][2], B0[2][2], B1[2][2];
;     const char* cA = (const char*)g.A + (size_t)cur.pm * tstep; const char* cB = (const char*)g.Bt + (size_t)cur.pn * tstep;
;     S.a_ready(cur);
;     if constexpr (SP2) {
;         PG8_STAGE(PG8_SB(0, 0), cB, voffB); PG8_STAGE(PG8_SB(0, 1), cB + hstep, voffB); PG8_STAGE(PG8_SA(0, 0), cA, voffA); PG8_STAGE(PG8_SA(0, 1), cA + hstep, voffA);
;         if (wr == 1) PG8_BAR;
;         PG8_WAIT_V(2); PG8_BAR;
;         PG8_STAGE(PG8_SB(1, 0), cB + kstep, voffB); PG8_STAGE(PG8_SA(1, 0), cA + kstep, voffA); PG8_STAGE(PG8_SB(1, 1), cB + hstep + kstep, voffB);
;         PG8_WAIT_V(6); PG8_BAR;
.LBB0_42:
	v_lshrrev_b32_e32 v18, 1, v16
	v_and_b32_e32 v18, 24, v18
	v_and_b32_e32 v17, 15, v16
	v_lshlrev_b32_e32 v19, 1, v18
	v_lshlrev_b32_e32 v16, 2, v16
	s_lshl_b32 s7, s7, 5
	v_lshl_or_b32 v138, s42, 6, v17
	v_lshl_or_b32 v17, v17, 6, v19
	s_lshl_b32 s42, s42, 13
	v_and_b32_e32 v16, 32, v16
	s_and_b32 s7, s7, 0x60
	s_add_i32 m0, s28, 0x18000
	v_lshl_add_u64 v[6:7], v[6:7], 0, s[30:31]
	v_bitop3_b32 v19, v17, s42, v16 bitop3:0xde
	s_lshl_b32 s42, s7, 7
	s_waitcnt vmcnt(2)
	s_barrier
	global_load_lds_dwordx4 v[6:7], off
	v_lshl_add_u64 v[4:5], v[4:5], 0, s[30:31]
	s_add_i32 m0, s28, 0x1a000
	s_add_i32 s74, s28, 0x8000
	s_add_i32 s75, s28, 0xa000
	v_bitop3_b32 v139, v17, s42, v16 bitop3:0xde
	global_load_lds_dwordx4 v[4:5], off
	v_lshl_add_u64 v[0:1], v[0:1], 0, s[30:31]
	s_mov_b32 m0, s74
	s_add_u32 s42, s4, 0x160080
	s_sext_i32_i8 s80, s43
	global_load_lds_dwordx4 v[0:1], off
	v_lshl_add_u64 v[0:1], v[2:3], 0, s[30:31]
	s_mov_b32 m0, s75
	s_addc_u32 s43, s5, 0
	global_load_lds_dwordx4 v[0:1], off
	s_add_i32 m0, s28, 0x1c000
	v_lshl_add_u64 v[0:1], s[42:43], 0, v[160:161]
	global_load_lds_dwordx4 v[0:1], off
	v_lshl_add_u64 v[0:1], s[42:43], 0, v[128:129]
	s_add_i32 m0, s28, 0x1e000
	s_movk_i32 s45, 0x1600
	global_load_lds_dwordx4 v[0:1], off
	v_lshrrev_b32_e32 v1, 1, v13
	v_mul_lo_u32 v0, v12, s45
	s_mov_b32 s44, 0x16000
	s_cmpk_lt_u32 s6, 0x100
	v_or_b32_e32 v140, s7, v18
	v_mad_u64_u32 v[0:1], s[6:7], v1, s44, v[0:1]
	v_or_b32_e32 v0, v0, v14
	v_add_lshl_u32 v0, v0, v15, 1
	v_mov_b32_e32 v1, v161
	s_mov_b64 s[52:53], 0x160080
	v_lshl_add_u64 v[134:135], v[0:1], 0, s[52:53]
	v_lshrrev_b32_e32 v1, 1, v8
	v_mul_lo_u32 v0, v9, s45
	v_mad_u64_u32 v[0:1], s[6:7], v1, s44, v[0:1]
	s_waitcnt vmcnt(6)
	v_or_b32_e32 v0, v0, v10
	v_add_lshl_u32 v0, v0, v11, 1
	v_mov_b32_e32 v1, v161
	s_cselect_b64 s[42:43], -1, 0
	v_lshl_add_u64 v[136:137], v[0:1], 0, s[52:53]
	v_readlane_b32 s98, v254, 19
	s_nop 3
	s_cmp_ge_u32 s98, 4
	s_cbranch_scc0 .Lyh_dn
	s_setprio 1
.Lyh_dn:
	s_mov_b32 s77, 0
	v_add_u32_e32 v141, 0, v19
	s_barrier
	s_branch .LBB0_45

;     __host__ __device__ bool next(int i, Unit& u) const { if (!base.next(i >> 1, u)) return false; if (i & 1) { u.pm += 64; u.pn += 8; } return true; }
; #define PG8_STAGE(bufoff, gbase, voff) do { _Pragma("unroll") for (int _i = 0; _i < 2; ++_i) \
;         __builtin_amdgcn_global_load_lds((const unsigned*)((const char*)(gbase) + (voff)[_i]), (PG8_LAS unsigned*)(lds + (bufoff) + ldsw + _i * 8192), 16, 0, 0); } while (0)
; #define PG8_WAIT_V(n) asm volatile("s_waitcnt vmcnt(" #n ")" ::: "memory")
; #define PG8_BAR __builtin_amdgcn_s_barrier()
; template <class Epi, class Sched, bool ALIGN_EPI = false, bool SP2 = false>
; __device__ __forceinline__ void gemm_phase(PG8_LAS unsigned char* lds, const Gemm g, const Sched& S, const Epi& E) {
;     ...
;     const int aoff = lds_byte(wr * 64 + fr, fq * 8), boff = lds_byte(wc * 32 + fr, fq * 8);
;     ...
;     Unit cur, nxt; int ui = 0;
;     if (!S.next(0, cur)) return;
;     f32x4 acc[2][2][4][2];
; #pragma unroll
;     for (int a = 0; a < 2; ++a)
; #pragma unroll
;         for (int b = 0; b < 2; ++b)
; #pragma unroll
;             for (int m = 0; m < 4; ++m)
; #pragma unroll
;                 for (int n = 0; n < 2; ++n) acc[a][b][m][n] = (f32x4){0.f, 0.f, 0.f, 0.f};
;     bf16x8 At[4][2], B0[2][2], B1[2][2];
;     const char* cA = (const char*)g.A + (size_t)cur.pm * tstep; const char* cB = (const char*)g.Bt + (size_t)cur.pn * tstep;
;     S.a_ready(cur);
;     if constexpr (SP2) {
;         PG8_STAGE(PG8_SB(0, 0), cB, voffB); PG8_STAGE(PG8_SB(0, 1), cB + hstep, voffB); PG8_STAGE(PG8_SA(0, 0), cA, voffA); PG8_STAGE(PG8_SA(0, 1), cA + hstep, voffA);
;         if (wr == 1) PG8_BAR;
;         PG8_WAIT_V(2); PG8_BAR;
;         PG8_STAGE(PG8_SB(1, 0), cB + kstep, voffB); PG8_STAGE(PG8_SA(1, 0), cA + kstep, voffA); PG8_STAGE(PG8_SB(1, 1), cB + hstep + kstep, voffB);
;         PG8_WAIT_V(6); PG8_BAR;
.LBB0_80:
	v_lshrrev_b32_e32 v16, 1, v6
	v_and_b32_e32 v16, 24, v16
	v_and_b32_e32 v7, 15, v6
	v_lshlrev_b32_e32 v17, 1, v16
	v_lshlrev_b32_e32 v6, 2, v6
	v_lshl_or_b32 v146, s13, 6, v7
	v_lshl_or_b32 v7, v7, 6, v17
	s_lshl_b32 s7, s13, 13
	v_and_b32_e32 v6, 32, v6
	v_bitop3_b32 v17, v7, s7, v6 bitop3:0xde
	s_lshl_b32 s7, s14, 5
	v_mov_b32_e32 v131, v161
	s_and_b32 s7, s7, 0x60
	v_lshl_add_u64 v[8:9], s[4:5], 0, v[130:131]
	v_mov_b32_e32 v135, v161
	s_lshl_b32 s13, s7, 7
	v_lshl_add_u64 v[10:11], s[4:5], 0, v[134:135]
	v_mov_b32_e32 v129, v161
	v_bitop3_b32 v147, v7, s13, v6 bitop3:0xde
	s_add_i32 m0, s63, 0x18000
	v_lshl_add_u64 v[6:7], v[8:9], 0, s[30:31]
	v_lshl_add_u64 v[12:13], s[52:53], 0, v[128:129]
	v_mov_b32_e32 v133, v161
	s_waitcnt vmcnt(2)
	s_barrier
	global_load_lds_dwordx4 v[6:7], off
	v_lshl_add_u64 v[6:7], v[10:11], 0, s[30:31]
	s_add_i32 m0, s63, 0x1a000
	s_add_i32 s84, s63, 0x8000
	s_add_i32 s85, s63, 0xa000
	v_lshl_add_u64 v[14:15], s[52:53], 0, v[132:133]
	global_load_lds_dwordx4 v[6:7], off
	v_lshl_add_u64 v[6:7], v[12:13], 0, s[30:31]
	s_mov_b32 m0, s84
	s_add_u32 s14, s4, 0x40080
	global_load_lds_dwordx4 v[6:7], off
	v_lshl_add_u64 v[6:7], v[14:15], 0, s[30:31]
	s_mov_b32 m0, s85
	s_addc_u32 s15, s5, 0
	global_load_lds_dwordx4 v[6:7], off
	s_add_i32 m0, s63, 0x1c000
	v_lshl_add_u64 v[6:7], s[14:15], 0, v[130:131]
	global_load_lds_dwordx4 v[6:7], off
	v_lshl_add_u64 v[6:7], s[14:15], 0, v[134:135]
	s_add_i32 m0, s63, 0x1e000
	s_cmpk_lt_u32 s12, 0x100
	global_load_lds_dwordx4 v[6:7], off
	v_lshlrev_b32_e32 v6, 14, v0
	v_and_b32_e32 v6, 0xffff8000, v6
	v_lshl_add_u32 v1, v1, 11, v6
	v_and_b32_e32 v0, 1, v0
	v_lshl_or_b32 v0, v0, 6, v1
	v_lshl_add_u32 v136, v2, 1, v0
	v_lshlrev_b32_e32 v0, 14, v3
	v_and_b32_e32 v0, 0xffff8000, v0
	s_waitcnt vmcnt(6)
	v_lshl_add_u32 v0, v4, 11, v0
	v_and_b32_e32 v1, 1, v3
	v_lshl_or_b32 v0, v1, 6, v0
	s_cselect_b64 s[12:13], -1, 0
	v_or_b32_e32 v148, s7, v16
	v_mov_b32_e32 v137, v161
	v_lshl_add_u32 v138, v5, 1, v0
	v_mov_b32_e32 v139, v161
	v_readlane_b32 s98, v254, 19
	s_nop 3
	s_cmp_ge_u32 s98, 4
	s_cbranch_scc0 .Lyh_br
	s_setprio 1
.Lyh_br:
	s_mov_b32 s7, 0
	v_add_u32_e32 v149, 0, v17
	s_barrier
	s_branch .LBB0_83

;     __host__ __device__ bool next(int i, Unit& u) const { if (!base.next(i >> 1, u)) return false; if (i & 1) { u.pm += 64; u.pn += 8; } return true; }
; #define PG8_STAGE(bufoff, gbase, voff) do { _Pragma("unroll") for (int _i = 0; _i < 2; ++_i) \
;         __builtin_amdgcn_global_load_lds((const unsigned*)((const char*)(gbase) + (voff)[_i]), (PG8_LAS unsigned*)(lds + (bufoff) + ldsw + _i * 8192), 16, 0, 0); } while (0)
; #define PG8_WAIT_V(n) asm volatile("s_waitcnt vmcnt(" #n ")" ::: "memory")
; #define PG8_BAR __builtin_amdgcn_s_barrier()
; template <class Epi, class Sched, bool ALIGN_EPI = false, bool SP2 = false>
; __device__ __forceinline__ void gemm_phase(PG8_LAS unsigned char* lds, const Gemm g, const Sched& S, const Epi& E) {
;     ...
;     const int aoff = lds_byte(wr * 64 + fr, fq * 8), boff = lds_byte(wc * 32 + fr, fq * 8);
;     ...
;     Unit cur, nxt; int ui = 0;
;     if (!S.next(0, cur)) return;
;     f32x4 acc[2][2][4][2];
; #pragma unroll
;     for (int a = 0; a < 2; ++a)
; #pragma unroll
;         for (int b = 0; b < 2; ++b)
; #pragma unroll
;             for (int m = 0; m < 4; ++m)
; #pragma unroll
;                 for (int n = 0; n < 2; ++n) acc[a][b][m][n] = (f32x4){0.f, 0.f, 0.f, 0.f};
;     bf16x8 At[4][2], B0[2][2], B1[2][2];
;     const char* cA = (const char*)g.A + (size_t)cur.pm * tstep; const char* cB = (const char*)g.Bt + (size_t)cur.pn * tstep;
;     S.a_ready(cur);
;     if constexpr (SP2) {
;         PG8_STAGE(PG8_SB(0, 0), cB, voffB); PG8_STAGE(PG8_SB(0, 1), cB + hstep, voffB); PG8_STAGE(PG8_SA(0, 0), cA, voffA); PG8_STAGE(PG8_SA(0, 1), cA + hstep, voffA);
;         if (wr == 1) PG8_BAR;
;         PG8_WAIT_V(2); PG8_BAR;
;         PG8_STAGE(PG8_SB(1, 0), cB + kstep, voffB); PG8_STAGE(PG8_SA(1, 0), cA + kstep, voffA); PG8_STAGE(PG8_SB(1, 1), cB + hstep + kstep, voffB);
;         PG8_WAIT_V(6); PG8_BAR;
.LBB0_316:
	s_add_u32 s80, s60, 0x100000
	s_addc_u32 s81, s61, 0
	s_and_b32 s42, s0, 3
	s_add_i32 m0, s89, 0x18000
	v_lshl_add_u64 v[4:5], v[4:5], 0, s[30:31]
	s_lshl_b32 s74, s6, 6
	s_lshl_b32 s28, s6, 13
	s_lshl_b32 s75, s42, 5
	s_lshl_b32 s0, s42, 12
	s_waitcnt vmcnt(2)
	s_barrier
	global_load_lds_dwordx4 v[4:5], off
	v_lshl_add_u64 v[2:3], v[2:3], 0, s[30:31]
	s_add_i32 m0, s89, 0x1a000
	s_add_i32 s78, s89, 0x8000
	s_add_i32 s79, s89, 0xa000
	global_load_lds_dwordx4 v[2:3], off
	v_lshl_add_u64 v[0:1], v[0:1], 0, s[30:31]
	s_mov_b32 m0, s78
	s_add_u32 s6, s4, 0x80080
	global_load_lds_dwordx4 v[0:1], off
	v_lshl_add_u64 v[0:1], v[6:7], 0, s[30:31]
	s_mov_b32 m0, s79
	s_addc_u32 s7, s5, 0
	global_load_lds_dwordx4 v[0:1], off
	s_add_i32 m0, s89, 0x1c000
	v_lshl_add_u64 v[0:1], s[6:7], 0, v[130:131]
	global_load_lds_dwordx4 v[0:1], off
	v_lshl_add_u64 v[0:1], s[6:7], 0, v[134:135]
	s_add_i32 m0, s89, 0x1e000
	s_cmpk_lt_u32 s1, 0x100
	global_load_lds_dwordx4 v[0:1], off
	v_bfe_u32 v0, v8, 4, 2
	s_cselect_b64 s[82:83], -1, 0
	s_cmp_eq_u32 s42, 0
	v_and_b32_e32 v137, 15, v8
	v_lshlrev_b32_e32 v1, 4, v0
	v_lshlrev_b32_e32 v2, 2, v8
	s_cselect_b64 s[84:85], -1, 0
	s_bitcmp0_b32 s1, 6
	v_lshl_or_b32 v1, v137, 6, v1
	v_and_b32_e32 v2, 32, v2
	s_cselect_b64 s[86:87], -1, 0
	s_lshl_b32 s1, s42, 11
	v_bitop3_b32 v4, v1, s28, v2 bitop3:0xde
	v_bitop3_b32 v139, v1, s0, v2 bitop3:0xde
	s_or_b32 s1, s28, s1
	v_lshlrev_b32_e32 v1, 6, v8
	v_cmp_gt_u32_e64 s[6:7], 2, v0
	v_cmp_lt_u32_e64 s[8:9], 1, v0
	v_cmp_eq_u32_e64 s[10:11], 0, v0
	v_lshl_or_b32 v141, v0, 3, s75
	s_add_i32 s1, s1, 0x20080
	v_and_b32_e32 v1, 0x400, v1
	v_lshlrev_b32_e32 v2, 1, v137
	v_lshlrev_b32_e32 v0, 5, v0
	v_or3_b32 v143, s1, v1, v2
	v_and_b32_e32 v1, 7, v8
	v_and_b32_e32 v160, 32, v0
	v_lshl_or_b32 v5, v1, 4, s1
	v_lshlrev_b32_e32 v136, 3, v1
	v_bfe_u32 v1, v8, 3, 3
	v_lshl_add_u64 v[2:3], s[60:61], 0, v[160:161]
	s_mov_b64 s[28:29], 0x140000
	s_lshl_b32 s1, s42, 7
	v_lshlrev_b32_e32 v6, 7, v1
	v_lshlrev_b32_e32 v138, 12, v1
	v_or_b32_e32 v1, 8, v1
	v_lshl_add_u64 v[146:147], v[2:3], 0, s[28:29]
	s_add_u32 s28, s60, s1
	v_lshlrev_b32_e32 v7, 7, v1
	v_lshlrev_b32_e32 v140, 12, v1
	s_addc_u32 s29, s61, 0
	v_mov_b32_e32 v1, v161
	v_lshl_add_u64 v[0:1], s[28:29], 0, v[0:1]
	s_mov_b64 s[28:29], 0x200000
	v_lshl_add_u64 v[148:149], v[0:1], 0, s[28:29]
	v_lshlrev_b32_e32 v0, 15, v9
	v_and_b32_e32 v0, 0xffff0000, v0
	v_lshl_add_u32 v0, v10, 12, v0
	v_and_b32_e32 v1, 1, v9
	v_lshl_or_b32 v0, v1, 6, v0
	v_lshl_add_u32 v150, v11, 1, v0
	v_lshlrev_b32_e32 v0, 15, v12
	v_and_b32_e32 v0, 0xffff0000, v0
	s_waitcnt vmcnt(6)
	v_lshl_add_u32 v0, v13, 12, v0
	v_and_b32_e32 v1, 1, v12
	v_cmp_eq_u32_e64 s[44:45], 0, v137
	v_lshl_or_b32 v0, v1, 6, v0
	v_readlane_b32 s98, v254, 19
	s_nop 3
	s_cmp_ge_u32 s98, 4
	s_cbranch_scc0 .Lyh_proj
	s_setprio 1
.Lyh_proj:
	s_mov_b32 s0, 0
	v_writelane_b32 v254, s44, 24
	v_or_b32_e32 v142, 0x10000, v138
	v_or_b32_e32 v144, 0x10000, v140
	v_mov_b32_e32 v151, v161
	v_lshl_add_u32 v152, v14, 1, v0
	v_mov_b32_e32 v153, v161
	v_add_u32_e32 v145, 0, v4
	v_add_u32_e32 v163, v5, v6
	v_add_u32_e32 v200, v5, v7
	s_barrier
	v_writelane_b32 v254, s45, 25
	s_branch .LBB0_319

;     __host__ __device__ bool next(int i, Unit& u) const { if (!base.next(i >> 1, u)) return false; if (i & 1) { u.pm += 64; u.pn += 8; } return true; }
; #define PG8_STAGE(bufoff, gbase, voff) do { _Pragma("unroll") for (int _i = 0; _i < 2; ++_i) \
;         __builtin_amdgcn_global_load_lds((const unsigned*)((const char*)(gbase) + (voff)[_i]), (PG8_LAS unsigned*)(lds + (bufoff) + ldsw + _i * 8192), 16, 0, 0); } while (0)
; #define PG8_WAIT_V(n) asm volatile("s_waitcnt vmcnt(" #n ")" ::: "memory")
; #define PG8_BAR __builtin_amdgcn_s_barrier()
; template <class Epi, class Sched, bool ALIGN_EPI = false, bool SP2 = false>
; __device__ __forceinline__ void gemm_phase(PG8_LAS unsigned char* lds, const Gemm g, const Sched& S, const Epi& E) {
;     ...
;     const int aoff = lds_byte(wr * 64 + fr, fq * 8), boff = lds_byte(wc * 32 + fr, fq * 8);
;     ...
;     Unit cur, nxt; int ui = 0;
;     if (!S.next(0, cur)) return;
;     f32x4 acc[2][2][4][2];
; #pragma unroll
;     for (int a = 0; a < 2; ++a)
; #pragma unroll
;         for (int b = 0; b < 2; ++b)
; #pragma unroll
;             for (int m = 0; m < 4; ++m)
; #pragma unroll
;                 for (int n = 0; n < 2; ++n) acc[a][b][m][n] = (f32x4){0.f, 0.f, 0.f, 0.f};
;     bf16x8 At[4][2], B0[2][2], B1[2][2];
;     const char* cA = (const char*)g.A + (size_t)cur.pm * tstep; const char* cB = (const char*)g.Bt + (size_t)cur.pn * tstep;
;     S.a_ready(cur);
;     if constexpr (SP2) {
;         PG8_STAGE(PG8_SB(0, 0), cB, voffB); PG8_STAGE(PG8_SB(0, 1), cB + hstep, voffB); PG8_STAGE(PG8_SA(0, 0), cA, voffA); PG8_STAGE(PG8_SA(0, 1), cA + hstep, voffA);
;         if (wr == 1) PG8_BAR;
;         PG8_WAIT_V(2); PG8_BAR;
;         PG8_STAGE(PG8_SB(1, 0), cB + kstep, voffB); PG8_STAGE(PG8_SA(1, 0), cA + kstep, voffA); PG8_STAGE(PG8_SB(1, 1), cB + hstep + kstep, voffB);
;         PG8_WAIT_V(6); PG8_BAR;
.LBB0_843:
	v_lshl_add_u64 v[8:9], s[4:5], 0, v[160:161]
	v_mov_b32_e32 v129, v161
	s_lshl_b32 s11, s11, 5
	v_lshl_add_u64 v[10:11], s[4:5], 0, v[128:129]
	v_mov_b32_e32 v133, v161
	s_and_b32 s11, s11, 0x60
	s_add_i32 m0, s51, 0x18000
	v_lshl_add_u64 v[8:9], v[8:9], 0, s[30:31]
	v_lshl_add_u64 v[12:13], s[52:53], 0, v[132:133]
	v_mov_b32_e32 v131, v161
	s_lshl_b32 s14, s10, 13
	s_lshl_b32 s15, s11, 7
	s_waitcnt vmcnt(2)
	s_barrier
	global_load_lds_dwordx4 v[8:9], off
	v_lshl_add_u64 v[8:9], v[10:11], 0, s[30:31]
	s_add_i32 m0, s51, 0x1a000
	s_add_i32 s58, s51, 0x8000
	s_add_i32 s59, s51, 0xa000
	v_lshl_add_u64 v[14:15], s[52:53], 0, v[130:131]
	global_load_lds_dwordx4 v[8:9], off
	v_lshl_add_u64 v[8:9], v[12:13], 0, s[30:31]
	s_mov_b32 m0, s58
	s_add_u32 s12, s4, 0x80080
	global_load_lds_dwordx4 v[8:9], off
	v_lshl_add_u64 v[8:9], v[14:15], 0, s[30:31]
	s_mov_b32 m0, s59
	s_addc_u32 s13, s5, 0
	global_load_lds_dwordx4 v[8:9], off
	s_add_i32 m0, s51, 0x1c000
	v_lshl_add_u64 v[8:9], s[12:13], 0, v[160:161]
	global_load_lds_dwordx4 v[8:9], off
	v_lshl_add_u64 v[8:9], s[12:13], 0, v[128:129]
	s_add_i32 m0, s51, 0x1e000
	v_and_b32_e32 v7, 15, v1
	global_load_lds_dwordx4 v[8:9], off
	v_lshrrev_b32_e32 v8, 1, v1
	v_and_b32_e32 v8, 24, v8
	v_lshlrev_b32_e32 v9, 1, v8
	v_lshlrev_b32_e32 v1, 2, v1
	v_lshl_or_b32 v140, s10, 6, v7
	v_lshl_or_b32 v7, v7, 6, v9
	v_and_b32_e32 v1, 32, v1
	v_bitop3_b32 v9, v7, s14, v1 bitop3:0xde
	v_bitop3_b32 v141, v7, s15, v1 bitop3:0xde
	v_lshlrev_b32_e32 v1, 15, v5
	v_and_b32_e32 v1, 0xffff0000, v1
	v_lshl_add_u32 v1, v4, 12, v1
	v_and_b32_e32 v4, 1, v5
	v_lshl_or_b32 v1, v4, 6, v1
	v_lshl_add_u32 v134, v6, 1, v1
	v_lshlrev_b32_e32 v1, 15, v0
	v_and_b32_e32 v1, 0xffff0000, v1
	s_waitcnt vmcnt(6)
	v_lshl_add_u32 v1, v2, 12, v1
	v_and_b32_e32 v0, 1, v0
	s_cmpk_lt_u32 s9, 0x100
	v_lshl_or_b32 v0, v0, 6, v1
	s_sext_i32_i16 s29, s8
	s_cselect_b64 s[8:9], -1, 0
	v_or_b32_e32 v142, s11, v8
	v_mov_b32_e32 v135, v161
	v_lshl_add_u32 v136, v3, 1, v0
	v_mov_b32_e32 v137, v161
	v_readlane_b32 s98, v254, 19
	s_nop 3
	s_cmp_ge_u32 s98, 4
	s_cbranch_scc0 .Lyh_gu
	s_setprio 1
.Lyh_gu:
	s_mov_b32 s28, 0
	v_add_u32_e32 v143, 0, v9
	s_barrier
	s_branch .LBB0_846

; #define LAS __attribute__((address_space(3)))
; #define LAS __attribute__((address_space(3)))
; __device__ __forceinline__ unsigned xb_xcc_id() { return (unsigned)__builtin_amdgcn_s_getreg((3 << 11) | 20) & 0xFu; }
; __device__ __forceinline__ void xcd_barrier(const XcdBarrier& b) {
;     asm volatile("s_waitcnt vmcnt(0)" ::: "memory");
;     __syncthreads();
;     if (threadIdx.x == 0) {
;         unsigned* bar = b.bar;
;         __builtin_amdgcn_s_waitcnt(0);
;         unsigned nloc = b.st[0], nx = b.st[1];
;         if (nloc == 0u) { xcd_barrier_complete(bar, b.x, nloc, nx); b.st[0] = nloc; b.st[1] = nx; }
; __global__ void __launch_bounds__(NTHR, 2) fwd_kernel(Params P) {
;     ...
;         if (ph + 1 < ph_hi) {
;             if (ph == ph_lo) { grid.sync(); (void)xcd_barrier_post((unsigned*)(ws + WS_BAR), (volatile LAS unsigned*)(lds + LDS_BARST)); }
;             else { XcdBarrier xb_; xb_.bar = (unsigned*)(ws + WS_BAR); xb_.x = xb_xcc_id(); xb_.st = (volatile LAS unsigned*)(lds + LDS_BARST); xcd_barrier(xb_); }
.LBB0_939:
	s_setprio 0
	s_add_i32 s0, s47, 1
	s_cmp_ge_i32 s0, s67
	s_cbranch_scc1 .LBB0_1009
	s_cmp_lg_u32 s47, s66
	s_mov_b64 s[4:5], -1
	s_cbranch_scc0 .LBB0_994
	s_getreg_b32 s1, hwreg(HW_REG_XCC_ID, 0, 4)
	s_waitcnt vmcnt(0)
	s_waitcnt vmcnt(0) lgkmcnt(0)
	s_barrier
	s_mov_b64 s[6:7], exec
	v_readlane_b32 s2, v254, 2
	v_readlane_b32 s3, v254, 3
	s_and_b64 s[2:3], s[6:7], s[2:3]
	s_mov_b64 exec, s[2:3]
	s_cbranch_execz .LBB0_993
	v_readlane_b32 s2, v254, 10
	s_waitcnt vmcnt(0) expcnt(0) lgkmcnt(0)
	s_and_b32 s1, s1, 15
	v_mov_b32_e32 v0, s2
	ds_read_b32 v2, v0
	v_readlane_b32 s2, v254, 11
	s_waitcnt lgkmcnt(0)
	v_cmp_ne_u32_e32 vcc, 0, v2
	v_mov_b32_e32 v0, s2
	ds_read_b32 v0, v0
	s_cbranch_vccnz .LBB0_957
	s_add_u32 s4, s60, 0x10200
	s_addc_u32 s5, s61, 0
	s_add_u32 s8, s60, 0x10400
	s_addc_u32 s9, s61, 0
	s_add_u32 s10, s60, 0x10500
	s_addc_u32 s11, s61, 0
	s_add_u32 s12, s60, 0x10600
	s_addc_u32 s13, s61, 0
	s_add_u32 s14, s60, 0x10700
	s_addc_u32 s15, s61, 0
	s_add_u32 s42, s60, 0x10800
	s_addc_u32 s43, s61, 0
	s_add_u32 s44, s60, 0x10900
	s_addc_u32 s45, s61, 0
	s_add_u32 s52, s60, 0x10a00
	s_addc_u32 s53, s61, 0
	s_add_u32 s54, s60, 0x10b00
	s_addc_u32 s55, s61, 0
	s_add_u32 s56, s60, 0x10c00
	s_addc_u32 s57, s61, 0
	s_add_u32 s58, s60, 0x10d00
	s_addc_u32 s59, s61, 0
	s_add_u32 s62, s60, 0x10e00
	s_addc_u32 s63, s61, 0
	s_add_u32 s64, s60, 0x10f00
	s_addc_u32 s65, s61, 0
	s_add_u32 s66, s60, 0x11000
	s_addc_u32 s67, s61, 0
	s_add_u32 s68, s60, 0x11100
	s_addc_u32 s69, s61, 0
	s_add_u32 s70, s60, 0x11200
	s_addc_u32 s71, s61, 0
	s_add_u32 s72, s60, 0x11300
	s_addc_u32 s73, s61, 0
	s_mov_b32 s2, 1
	v_readlane_b32 s24, v254, 4
	s_branch .LBB0_945
